# p3b_rebalance_a1
# baseline (speedup 1.0000x reference)
.LBB0_1029:
	s_cmpk_gt_i32 s2, 0xfff
	s_cbranch_scc1 .LBB0_1032
	s_movk_i32 s96, 0x100
	s_cmpk_lt_u32 s2, 0x100
	s_movk_i32 s97, 0x1000
	s_cselect_b32 s97, s96, s97
	s_cmpk_eq_i32 s22, 0x200
	s_cselect_b32 s96, s96, s22
	s_cselect_b32 s97, s97, 0x1000
	s_add_u32 s15, s20, 0x17348000
	s_addc_u32 s16, s21, 0
	s_waitcnt vmcnt(30)
	v_mbcnt_hi_u32_b32 v20, -1, v183
	s_add_u32 s17, s20, 0x15248000
	v_and_b32_e32 v0, 64, v20
	s_mov_b32 s0, 0x358637bd
	s_addc_u32 s29, s21, 0
	s_mov_b32 s9, 0
	v_mov_b32_e32 v9, 0
	s_mov_b64 s[10:11], 0x1000
	s_mov_b64 s[12:13], 0x1800
	s_movk_i32 s34, 0x1000
	v_xor_b32_e32 v21, 1, v20
	v_add_u32_e32 v22, 64, v0
	v_xor_b32_e32 v23, 2, v20
	s_waitcnt vmcnt(29)
	v_xor_b32_e32 v24, 4, v20
	v_xor_b32_e32 v25, 8, v20
	s_mov_b32 s14, 0x3c800000
	v_mov_b64_e32 v[10:11], s[0:1]
	s_mov_b32 s35, 0x800000
	s_movk_i32 s36, 0x2000
	s_movk_i32 s37, 0x4000
	s_movk_i32 s38, 0x6000
	s_mov_b32 s39, s2
.LBB0_1031:
	v_cmp_lt_i32_e32 vcc, v21, v22
	v_mov_b32_e32 v0, v181
	s_ashr_i32 s0, s39, 3
	v_cndmask_b32_e32 v2, v20, v21, vcc
	v_cmp_lt_i32_e32 vcc, v23, v22
	s_waitcnt vmcnt(28)
	v_lshlrev_b32_e32 v33, 2, v2
	v_ashrrev_i32_e32 v2, 6, v0
	v_cndmask_b32_e32 v3, v20, v23, vcc
	v_cmp_lt_i32_e32 vcc, v24, v22
	v_lshlrev_b32_e32 v32, 2, v3
	v_and_b32_e32 v3, 63, v0
	v_cndmask_b32_e32 v4, v20, v24, vcc
	v_cmp_lt_i32_e32 vcc, v25, v22
	v_lshlrev_b32_e32 v31, 2, v4
	v_and_b32_e32 v4, 15, v0
	v_cndmask_b32_e32 v5, v20, v25, vcc
	v_lshlrev_b32_e32 v30, 2, v5
	v_lshrrev_b32_e32 v0, 2, v0
	v_lshlrev_b32_e32 v5, 4, v2
	s_lshl_b32 s1, s39, 7
	v_and_b32_e32 v6, 12, v0
	v_lshlrev_b32_e32 v7, 2, v3
	v_lshlrev_b32_e32 v12, 5, v3
	v_lshl_add_u32 v3, s0, 6, v5
	s_and_b32 s4, s39, 0xfffffc00
	s_and_b32 s8, s1, 0x380
	v_lshlrev_b32_e32 v8, 1, v4
	v_lshlrev_b32_e32 v0, 2, v4
	v_or_b32_e32 v5, v5, v4
	v_or_b32_e32 v4, v3, v6
	s_and_b32 s1, s0, 0x7f
	s_or_b32 s4, s8, s4
	global_load_dword v29, v0, s[40:41]
	global_load_dword v28, v0, s[40:41] offset:64
	global_load_dword v27, v0, s[40:41] offset:128
	global_load_dword v26, v0, s[40:41] offset:192
	v_lshlrev_b32_e32 v0, 1, v6
	v_lshlrev_b32_e32 v6, 6, v5
	v_ashrrev_i32_e32 v5, 31, v4
	s_or_b32 s4, s4, s1
	s_waitcnt vmcnt(28)
	v_lshlrev_b64 v[66:67], 13, v[4:5]
	s_ashr_i32 s5, s4, 31
	v_or_b32_e32 v14, 1, v4
	v_or_b32_e32 v16, 2, v4
	v_or_b32_e32 v18, 3, v4
	v_lshl_add_u64 v[4:5], s[20:21], 0, v[66:67]
	s_lshl_b64 s[0:1], s[4:5], 13
	v_lshl_add_u64 v[4:5], v[4:5], 0, s[8:9]
	s_add_u32 s4, s50, s0
	v_lshl_add_u64 v[50:51], v[4:5], 0, v[8:9]
	s_addc_u32 s5, s51, s1
	v_add_co_u32_e32 v52, vcc, s36, v50
	s_add_u32 s6, s17, s0
	s_nop 0
	v_addc_co_u32_e32 v53, vcc, 0, v51, vcc
	v_lshl_or_b32 v2, v2, 10, v7
	v_ashrrev_i32_e32 v7, 31, v6
	s_addc_u32 s7, s29, s1
	v_add_co_u32_e32 v54, vcc, s37, v50
	v_mov_b32_e32 v1, v9
	v_ashrrev_i32_e32 v3, 31, v2
	v_lshl_add_u64 v[6:7], v[6:7], 1, s[4:5]
	s_add_u32 s0, s15, s0
	v_addc_co_u32_e32 v55, vcc, 0, v51, vcc
	v_mov_b32_e32 v13, v9
	v_lshl_add_u64 v[34:35], v[6:7], 0, v[0:1]
	v_lshl_add_u64 v[36:37], v[2:3], 1, s[6:7]
	s_addc_u32 s1, s16, s1
	v_add_co_u32_e32 v56, vcc, s38, v50
	global_load_dwordx2 v[4:5], v[34:35], off
	global_load_dwordx2 v[6:7], v[34:35], off offset:32
	global_load_dwordx2 v[0:1], v[34:35], off offset:64
	global_load_dwordx2 v[2:3], v[34:35], off offset:96
	global_load_dwordx2 v[68:69], v[36:37], off
	global_load_dwordx2 v[72:73], v[36:37], off offset:512
	global_load_dwordx2 v[76:77], v[36:37], off offset:1024
	global_load_dwordx2 v[80:81], v[36:37], off offset:1536
	v_addc_co_u32_e32 v57, vcc, 0, v51, vcc
	global_load_ushort v82, v[50:51], off offset:3072
	global_load_ushort v83, v[50:51], off offset:3104
	global_load_ushort v84, v[50:51], off offset:3136
	global_load_ushort v85, v[50:51], off offset:3168
	global_load_dwordx4 v[34:37], v12, s[0:1]
	global_load_dwordx4 v[38:41], v12, s[0:1] offset:2048
	global_load_dwordx4 v[42:45], v12, s[0:1] offset:16
	global_load_dwordx4 v[46:49], v12, s[0:1] offset:2064
	global_load_ushort v86, v[52:53], off offset:3072
	global_load_ushort v87, v[54:55], off offset:3072
	global_load_ushort v88, v[56:57], off offset:3072
	global_load_ushort v89, v[52:53], off offset:3104
	global_load_ushort v90, v[54:55], off offset:3104
	global_load_ushort v91, v[56:57], off offset:3104
	global_load_ushort v92, v[52:53], off offset:3136
	global_load_ushort v93, v[54:55], off offset:3136
	global_load_ushort v94, v[56:57], off offset:3136
	global_load_ushort v95, v[54:55], off offset:3168
	global_load_ushort v96, v[52:53], off offset:3168
	global_load_ushort v97, v[56:57], off offset:3168
	v_lshl_add_u64 v[12:13], s[0:1], 0, v[12:13]
	v_lshl_add_u64 v[70:71], v[12:13], 0, s[10:11]
	s_waitcnt vmcnt(55)
	v_lshl_add_u64 v[74:75], v[12:13], 0, s[12:13]
	v_add_co_u32_e32 v12, vcc, s34, v12
	s_add_u32 s0, s20, s8
	s_nop 0
	v_addc_co_u32_e32 v13, vcc, 0, v13, vcc
	global_load_dwordx4 v[50:53], v[12:13], off
	global_load_dwordx4 v[54:57], v[12:13], off offset:2048
	global_load_dwordx4 v[58:61], v[70:71], off offset:16
	global_load_dwordx4 v[62:65], v[74:75], off offset:16
	s_addc_u32 s1, s21, 0
	v_ashrrev_i32_e32 v15, 31, v14
	v_ashrrev_i32_e32 v17, 31, v16
	v_ashrrev_i32_e32 v19, 31, v18
	v_lshl_add_u64 v[70:71], s[0:1], 0, v[8:9]
	v_lshlrev_b64 v[14:15], 13, v[14:15]
	v_lshlrev_b64 v[16:17], 13, v[16:17]
	v_lshlrev_b64 v[18:19], 13, v[18:19]
	v_lshl_add_u64 v[12:13], v[70:71], 0, v[66:67]
	v_lshl_add_u64 v[14:15], v[70:71], 0, v[14:15]
	v_lshl_add_u64 v[16:17], v[70:71], 0, v[16:17]
	v_lshl_add_u64 v[18:19], v[70:71], 0, v[18:19]
	s_add_i32 s39, s39, s96
	s_cmp_lt_i32 s39, s97
	s_waitcnt vmcnt(23)
	v_lshlrev_b32_e32 v8, 16, v82
	s_waitcnt vmcnt(22)
	v_lshlrev_b32_e32 v98, 16, v83
	s_waitcnt vmcnt(21)
	v_lshlrev_b32_e32 v99, 16, v84
	s_waitcnt vmcnt(20)
	v_lshlrev_b32_e32 v100, 16, v85
	s_waitcnt vmcnt(19)
	v_mov_b32_e32 v82, v34
	v_mov_b32_e32 v83, v35
	s_waitcnt vmcnt(18)
	v_mov_b32_e32 v84, v38
	v_mov_b32_e32 v85, v39
	s_waitcnt vmcnt(17)
	v_mov_b32_e32 v34, v42
	v_mov_b32_e32 v35, v43
	v_mul_f32_e32 v42, 0xbfb8aa3b, v8
	v_mul_f32_e32 v43, 0xbfb8aa3b, v98
	v_mov_b32_e32 v38, v36
	v_mov_b32_e32 v39, v37
	v_lshlrev_b32_e32 v66, 16, v68
	v_and_b32_e32 v67, 0xffff0000, v68
	v_lshlrev_b32_e32 v68, 16, v69
	v_and_b32_e32 v69, 0xffff0000, v69
	v_lshlrev_b32_e32 v70, 16, v72
	v_and_b32_e32 v71, 0xffff0000, v72
	v_lshlrev_b32_e32 v72, 16, v73
	v_and_b32_e32 v73, 0xffff0000, v73
	s_waitcnt vmcnt(16)
	v_mov_b32_e32 v36, v46
	v_mov_b32_e32 v37, v47
	v_mov_b32_e32 v46, v44
	v_mov_b32_e32 v47, v45
	v_exp_f32_e32 v103, v42
	v_exp_f32_e32 v107, v43
	v_mfma_f32_16x16x32_bf16 v[42:45], v[4:7], v[82:85], v[66:69]
	v_lshlrev_b32_e32 v74, 16, v76
	v_and_b32_e32 v75, 0xffff0000, v76
	v_lshlrev_b32_e32 v76, 16, v77
	v_and_b32_e32 v77, 0xffff0000, v77
	v_lshlrev_b32_e32 v78, 16, v80
	v_and_b32_e32 v79, 0xffff0000, v80
	v_lshlrev_b32_e32 v80, 16, v81
	v_and_b32_e32 v81, 0xffff0000, v81
	s_waitcnt vmcnt(15)
	v_lshlrev_b32_e32 v86, 16, v86
	s_waitcnt vmcnt(14)
	v_lshlrev_b32_e32 v87, 16, v87
	v_mul_f32_e32 v101, 0xbfb8aa3b, v99
	v_mfma_f32_16x16x32_bf16 v[38:41], v[4:7], v[38:41], v[70:73]
	s_waitcnt vmcnt(8)
	v_lshlrev_b32_e32 v93, 16, v93
	s_waitcnt vmcnt(7)
	v_lshlrev_b32_e32 v94, 16, v94
	v_mul_f32_e32 v104, 0xbfb8aa3b, v86
	v_mul_f32_e32 v105, 0xbfb8aa3b, v87
	v_exp_f32_e32 v67, v101
	v_mfma_f32_16x16x32_bf16 v[34:37], v[4:7], v[34:37], v[74:77]
	v_lshlrev_b32_e32 v88, 16, v88
	v_lshlrev_b32_e32 v89, 16, v89
	v_lshlrev_b32_e32 v90, 16, v90
	v_mfma_f32_16x16x32_bf16 v[4:7], v[4:7], v[46:49], v[78:81]
	v_lshlrev_b32_e32 v92, 16, v92
	s_waitcnt vmcnt(5)
	v_lshlrev_b32_e32 v96, 16, v96
	v_lshlrev_b32_e32 v95, 16, v95
	v_mul_f32_e32 v69, 0xbfb8aa3b, v93
	v_mul_f32_e32 v70, 0xbfb8aa3b, v94
	s_waitcnt vmcnt(3)
	v_mov_b32_e32 v46, v50
	v_mov_b32_e32 v47, v51
	s_waitcnt vmcnt(2)
	v_mov_b32_e32 v48, v54
	v_mov_b32_e32 v49, v55
	s_waitcnt vmcnt(1)
	v_mov_b32_e32 v50, v58
	v_mov_b32_e32 v51, v59
	v_exp_f32_e32 v58, v104
	v_exp_f32_e32 v59, v105
	v_lshlrev_b32_e32 v91, 16, v91
	v_mul_f32_e32 v102, 0xbfb8aa3b, v100
	v_lshlrev_b32_e32 v97, 16, v97
	v_mul_f32_e32 v106, 0xbfb8aa3b, v88
	v_mul_f32_e32 v108, 0xbfb8aa3b, v89
	v_mul_f32_e32 v109, 0xbfb8aa3b, v90
	v_mul_f32_e32 v68, 0xbfb8aa3b, v92
	v_mul_f32_e32 v72, 0xbfb8aa3b, v96
	v_mul_f32_e32 v73, 0xbfb8aa3b, v95
	v_mov_b32_e32 v54, v52
	v_mov_b32_e32 v55, v53
	v_mfma_f32_16x16x32_bf16 v[42:45], v[0:3], v[46:49], v[42:45]
	v_exp_f32_e32 v46, v69
	v_exp_f32_e32 v47, v70
	v_mul_f32_e32 v66, 0xbfb8aa3b, v91
	v_exp_f32_e32 v71, v102
	v_mul_f32_e32 v74, 0xbfb8aa3b, v97
	s_waitcnt vmcnt(0)
	v_mov_b32_e32 v52, v62
	v_mov_b32_e32 v53, v63
	v_mov_b32_e32 v62, v60
	v_mov_b32_e32 v63, v61
	v_exp_f32_e32 v60, v106
	v_exp_f32_e32 v61, v108
	v_exp_f32_e32 v75, v109
	v_exp_f32_e32 v68, v68
	v_exp_f32_e32 v48, v72
	v_mfma_f32_16x16x32_bf16 v[38:41], v[0:3], v[54:57], v[38:41]
	v_exp_f32_e32 v49, v73
	v_exp_f32_e32 v66, v66
	v_exp_f32_e32 v54, v74
	v_add_f32_e32 v55, 1.0, v103
	v_mfma_f32_16x16x32_bf16 v[34:37], v[0:3], v[50:53], v[34:37]
	v_add_f32_e32 v50, 1.0, v107
	v_add_f32_e32 v51, 1.0, v67
	v_add_f32_e32 v46, 1.0, v46
	v_mfma_f32_16x16x32_bf16 v[0:3], v[0:3], v[62:65], v[4:7]
	v_rcp_f32_e32 v62, v55
	v_add_f32_e32 v47, 1.0, v47
	v_add_f32_e32 v52, 1.0, v71
	v_add_f32_e32 v4, 1.0, v58
	v_add_f32_e32 v5, 1.0, v59
	v_rcp_f32_e32 v58, v50
	v_rcp_f32_e32 v59, v51
	v_add_f32_e32 v6, 1.0, v60
	v_add_f32_e32 v7, 1.0, v61
	v_add_f32_e32 v50, 1.0, v75
	v_add_f32_e32 v51, 1.0, v68
	v_add_f32_e32 v48, 1.0, v48
	v_add_f32_e32 v49, 1.0, v49
	v_rcp_f32_e32 v61, v4
	v_rcp_f32_e32 v63, v5
	v_rcp_f32_e32 v69, v46
	v_rcp_f32_e32 v70, v47
	v_mov_b32_e32 v4, v42
	v_mov_b32_e32 v5, v38
	v_mov_b32_e32 v46, v43
	v_mov_b32_e32 v47, v39
	v_add_f32_e32 v53, 1.0, v66
	v_rcp_f32_e32 v60, v52
	v_add_f32_e32 v52, 1.0, v54
	v_rcp_f32_e32 v64, v6
	v_rcp_f32_e32 v65, v7
	v_rcp_f32_e32 v66, v50
	v_rcp_f32_e32 v68, v51
	v_rcp_f32_e32 v71, v48
	v_rcp_f32_e32 v72, v49
	v_mov_b32_e32 v6, v34
	v_mov_b32_e32 v7, v0
	v_mov_b32_e32 v48, v35
	v_mov_b32_e32 v49, v1
	v_mov_b32_e32 v50, v44
	v_mov_b32_e32 v51, v40
	v_mov_b32_e32 v54, v45
	v_mov_b32_e32 v55, v41
	v_pk_mul_f32 v[4:5], v[4:5], v[4:5]
	v_pk_mul_f32 v[46:47], v[46:47], v[46:47]
	v_rcp_f32_e32 v67, v53
	v_rcp_f32_e32 v73, v52
	v_mov_b32_e32 v52, v36
	v_mov_b32_e32 v53, v2
	v_mov_b32_e32 v56, v37
	v_mov_b32_e32 v57, v3
	v_mul_f32_e32 v8, v62, v8
	v_mul_f32_e32 v62, v58, v98
	v_mul_f32_e32 v74, v59, v99
	v_pk_mul_f32 v[6:7], v[6:7], v[6:7]
	v_pk_mul_f32 v[48:49], v[48:49], v[48:49]
	v_pk_mul_f32 v[50:51], v[50:51], v[50:51]
	v_pk_mul_f32 v[54:55], v[54:55], v[54:55]
	v_mov_b32_e32 v58, v46
	v_mov_b32_e32 v59, v4
	v_mov_b32_e32 v4, v47
	v_pk_mul_f32 v[52:53], v[52:53], v[52:53]
	v_pk_mul_f32 v[56:57], v[56:57], v[56:57]
	v_mov_b32_e32 v46, v48
	v_mov_b32_e32 v47, v6
	v_mov_b32_e32 v6, v49
	v_mov_b32_e32 v48, v54
	v_mov_b32_e32 v49, v50
	v_mov_b32_e32 v50, v55
	v_pk_add_f32 v[4:5], v[58:59], v[4:5]
	v_mov_b32_e32 v54, v56
	v_mov_b32_e32 v55, v52
	v_pk_add_f32 v[48:49], v[48:49], v[50:51]
	v_pk_add_f32 v[4:5], v[4:5], v[46:47]
	v_mov_b32_e32 v52, v57
	v_pk_add_f32 v[46:47], v[48:49], v[54:55]
	v_pk_add_f32 v[4:5], v[4:5], v[6:7]
	v_pk_add_f32 v[6:7], v[46:47], v[52:53]
	ds_bpermute_b32 v47, v33, v5
	ds_bpermute_b32 v46, v33, v4
	ds_bpermute_b32 v49, v33, v7
	ds_bpermute_b32 v48, v33, v6
	v_mul_f32_e32 v60, v60, v100
	v_mul_f32_e32 v61, v61, v86
	s_waitcnt lgkmcnt(2)
	v_pk_add_f32 v[4:5], v[4:5], v[46:47]
	ds_bpermute_b32 v47, v32, v5
	s_waitcnt lgkmcnt(1)
	v_pk_add_f32 v[6:7], v[6:7], v[48:49]
	ds_bpermute_b32 v46, v32, v4
	ds_bpermute_b32 v33, v32, v7
	ds_bpermute_b32 v32, v32, v6
	v_mul_f32_e32 v63, v63, v87
	v_mul_f32_e32 v64, v64, v88
	s_waitcnt lgkmcnt(2)
	v_pk_add_f32 v[4:5], v[4:5], v[46:47]
	v_mul_f32_e32 v65, v65, v89
	s_waitcnt lgkmcnt(0)
	v_pk_add_f32 v[6:7], v[6:7], v[32:33]
	ds_bpermute_b32 v33, v31, v5
	ds_bpermute_b32 v32, v31, v4
	ds_bpermute_b32 v47, v31, v7
	ds_bpermute_b32 v46, v31, v6
	v_mul_f32_e32 v66, v66, v90
	v_mul_f32_e32 v67, v67, v91
	s_waitcnt lgkmcnt(2)
	v_pk_add_f32 v[4:5], v[4:5], v[32:33]
	ds_bpermute_b32 v33, v30, v5
	s_waitcnt lgkmcnt(1)
	v_pk_add_f32 v[6:7], v[6:7], v[46:47]
	ds_bpermute_b32 v32, v30, v4
	ds_bpermute_b32 v31, v30, v7
	ds_bpermute_b32 v30, v30, v6
	v_mul_f32_e32 v68, v68, v92
	v_mul_f32_e32 v69, v69, v93
	s_waitcnt lgkmcnt(2)
	v_pk_add_f32 v[4:5], v[4:5], v[32:33]
	v_mul_f32_e32 v70, v70, v94
	s_waitcnt lgkmcnt(0)
	v_pk_add_f32 v[6:7], v[6:7], v[30:31]
	v_pk_fma_f32 v[4:5], v[4:5], s[14:15], v[10:11] op_sel_hi:[1,0,0]
	v_pk_fma_f32 v[6:7], v[6:7], s[14:15], v[10:11] op_sel_hi:[1,0,0]
	v_mul_f32_e32 v30, 0x4b800000, v5
	v_cmp_gt_f32_e64 s[6:7], s35, v5
	v_mul_f32_e32 v31, 0x4b800000, v4
	v_cmp_gt_f32_e32 vcc, s35, v4
	v_mul_f32_e32 v32, 0x4b800000, v7
	v_mul_f32_e32 v33, 0x4b800000, v6
	v_cmp_gt_f32_e64 s[0:1], s35, v6
	v_cmp_gt_f32_e64 s[4:5], s35, v7
	v_cndmask_b32_e64 v5, v5, v30, s[6:7]
	v_cndmask_b32_e32 v4, v4, v31, vcc
	v_cndmask_b32_e64 v7, v7, v32, s[4:5]
	v_cndmask_b32_e64 v6, v6, v33, s[0:1]
	v_rsq_f32_e32 v5, v5
	v_rsq_f32_e32 v4, v4
	v_rsq_f32_e32 v7, v7
	v_rsq_f32_e32 v6, v6
	v_mul_f32_e32 v30, 0x45800000, v5
	v_mul_f32_e32 v31, 0x45800000, v4
	v_mul_f32_e32 v32, 0x45800000, v7
	v_mul_f32_e32 v33, 0x45800000, v6
	v_cndmask_b32_e64 v5, v5, v30, s[6:7]
	v_cndmask_b32_e32 v4, v4, v31, vcc
	v_cndmask_b32_e64 v7, v7, v32, s[4:5]
	v_cndmask_b32_e64 v6, v6, v33, s[0:1]
	v_mul_f32_e32 v30, v42, v5
	v_mul_f32_e32 v31, v43, v4
	v_mul_f32_e32 v32, v44, v7
	v_mul_f32_e32 v33, v45, v6
	v_mul_f32_e32 v38, v38, v5
	v_mul_f32_e32 v39, v39, v4
	v_mul_f32_e32 v40, v40, v7
	v_mul_f32_e32 v41, v41, v6
	v_mul_f32_e32 v34, v34, v5
	v_mul_f32_e32 v35, v35, v4
	v_mul_f32_e32 v36, v36, v7
	v_mul_f32_e32 v37, v37, v6
	v_mul_f32_e32 v0, v0, v5
	v_mul_f32_e32 v1, v1, v4
	v_mul_f32_e32 v2, v2, v7
	v_mul_f32_e32 v3, v3, v6
	v_mul_f32_e32 v4, v29, v30
	v_mul_f32_e32 v71, v71, v96
	v_mul_f32_e32 v72, v72, v95
	v_mul_f32_e32 v73, v73, v97
	v_mul_f32_e32 v5, v29, v31
	v_mul_f32_e32 v6, v29, v32
	v_mul_f32_e32 v7, v29, v33
	v_mul_f32_e32 v29, v28, v38
	v_mul_f32_e32 v30, v28, v39
	v_mul_f32_e32 v31, v28, v40
	v_mul_f32_e32 v28, v28, v41
	v_mul_f32_e32 v32, v27, v34
	v_mul_f32_e32 v33, v27, v35
	v_mul_f32_e32 v34, v27, v36
	v_mul_f32_e32 v27, v27, v37
	v_mul_f32_e32 v0, v26, v0
	v_mul_f32_e32 v1, v26, v1
	v_mul_f32_e32 v2, v26, v2
	v_mul_f32_e32 v3, v26, v3
	v_mul_f32_e32 v4, v8, v4
	v_mul_f32_e32 v5, v61, v5
	v_mul_f32_e32 v6, v63, v6
	v_mul_f32_e32 v7, v64, v7
	v_mul_f32_e32 v8, v62, v29
	v_mul_f32_e32 v26, v65, v30
	v_mul_f32_e32 v29, v66, v31
	v_mul_f32_e32 v28, v67, v28
	v_mul_f32_e32 v30, v74, v32
	v_mul_f32_e32 v31, v68, v33
	v_mul_f32_e32 v32, v69, v34
	v_mul_f32_e32 v27, v70, v27
	v_mul_f32_e32 v0, v60, v0
	v_mul_f32_e32 v1, v71, v1
	v_mul_f32_e32 v2, v72, v2
	v_mul_f32_e32 v3, v73, v3
	v_cvt_pk_bf16_f32 v4, v4, s0
	v_cvt_pk_bf16_f32 v5, v5, s0
	v_cvt_pk_bf16_f32 v6, v6, s0
	v_cvt_pk_bf16_f32 v7, v7, s0
	v_cvt_pk_bf16_f32 v8, v8, s0
	v_cvt_pk_bf16_f32 v26, v26, s0
	v_cvt_pk_bf16_f32 v29, v29, s0
	v_cvt_pk_bf16_f32 v28, v28, s0
	v_cvt_pk_bf16_f32 v30, v30, s0
	v_cvt_pk_bf16_f32 v31, v31, s0
	v_cvt_pk_bf16_f32 v32, v32, s0
	v_cvt_pk_bf16_f32 v27, v27, s0
	v_cvt_pk_bf16_f32 v0, v0, s0
	v_cvt_pk_bf16_f32 v1, v1, s0
	v_cvt_pk_bf16_f32 v2, v2, s0
	v_cvt_pk_bf16_f32 v3, v3, s0
	global_store_short v[12:13], v4, off
	global_store_short v[14:15], v5, off
	global_store_short v[16:17], v6, off
	global_store_short v[18:19], v7, off
	global_store_short v[12:13], v8, off offset:32
	global_store_short v[14:15], v26, off offset:32
	global_store_short v[16:17], v29, off offset:32
	global_store_short v[18:19], v28, off offset:32
	global_store_short v[12:13], v30, off offset:64
	global_store_short v[14:15], v31, off offset:64
	global_store_short v[16:17], v32, off offset:64
	global_store_short v[18:19], v27, off offset:64
	global_store_short v[12:13], v0, off offset:96
	global_store_short v[14:15], v1, off offset:96
	global_store_short v[16:17], v2, off offset:96
	global_store_short v[18:19], v3, off offset:96
	s_cbranch_scc1 .LBB0_1031
